# hbkeep11: 11 of 16 bf16 h blocks kept in VGPRs from P3 to P4 (out-pointer load moved off v250/251 to free them)
# speedup vs baseline: 1.0084x; 1.0004x over previous
; __device__ __forceinline__ unsigned cvtpk(float lo, float hi) { f32x2 v = {lo, hi}; bf16x2_t b = __builtin_convertvector(v, bf16x2_t); return __builtin_bit_cast(unsigned, b); }
;     __device__ __forceinline__ void operator()(const Acc& acc, const Unit& u, int wr, int wc, int fr, int fq) const {
;     ...
;             for (int m = 0; m < 4; ++m) { const size_t off = (size_t)(u.pm * 256 + ai * 128 + wr * 64 + m * 16 + fr) * DM + colbase;
; #pragma unroll
;                 for (int bj = 0; bj < 2; ++bj) { xv[m][bj][0] = __builtin_nontemporal_load((const f32x4*)(x + off + 32 * bj)); xv[m][bj][1] = __builtin_nontemporal_load((const f32x4*)(x + off + 32 * bj + 4)); } }
; #pragma unroll
;             for (int m = 0; m < 4; ++m) {
;                 const int row = u.pm * 256 + ai * 128 + wr * 64 + m * 16 + fr;
;                 float ss = 0.f;
; #pragma unroll
;                 for (int bj = 0; bj < 2; ++bj) {
;                     const size_t off = (size_t)row * DM + colbase + 32 * bj;
;                     const f32x4 h0 = xv[m][bj][0] + acc[ai][bj][m][0], h1 = xv[m][bj][1] + acc[ai][bj][m][1];
;                     u32x4 w; w.x = cvtpk(h0.x, h0.y); w.y = cvtpk(h0.z, h0.w); w.z = cvtpk(h1.x, h1.y); w.w = cvtpk(h1.z, h1.w);
;                     *(u32x4*)(HB + off) = w;
;                     ss += (h0.x * h0.x + h0.y * h0.y) + (h0.z * h0.z + h0.w * h0.w) + (h1.x * h1.x + h1.y * h1.y) + (h1.z * h1.z + h1.w * h1.w);
;                 }
;                 ss = quad_sum(ss);
;                 if (fq == 0) atomicAdd(rowss + row, ss);
.LBB0_735:
	s_or_b64 exec, exec, s[20:21]
	v_lshlrev_b64 v[48:49], 12, v[118:119]
	v_pk_add_f32 v[46:47], v[46:47], v[110:111]
	v_pk_add_f32 v[44:45], v[44:45], v[108:109]
	v_pk_add_f32 v[50:51], v[42:43], v[106:107]
	v_pk_add_f32 v[52:53], v[40:41], v[104:105]
	v_lshl_add_u64 v[48:49], s[10:11], 0, v[48:49]
	v_cvt_pk_bf16_f32 v40, v44, v45
	v_cvt_pk_bf16_f32 v41, v46, v47
	v_cvt_pk_bf16_f32 v42, v52, v53
	v_cvt_pk_bf16_f32 v43, v50, v51
	v_lshl_add_u64 v[48:49], v[188:189], 1, v[48:49]
	v_mov_b64_e32 v[222:223], v[40:41]
	v_mov_b64_e32 v[250:251], v[42:43]
	flat_store_dwordx4 v[48:49], v[40:43]
	v_pk_add_f32 v[36:37], v[36:37], v[100:101]
	v_pk_add_f32 v[38:39], v[38:39], v[102:103]
	v_mul_f32_e32 v40, v45, v45
	v_mul_f32_e32 v41, v47, v47
	v_fmac_f32_e32 v40, v44, v44
	v_fmac_f32_e32 v41, v46, v46
	v_add_f32_e32 v40, v40, v41
	v_mul_f32_e32 v41, v53, v53
	v_fmac_f32_e32 v41, v52, v52
	v_add_f32_e32 v40, v40, v41
	v_mul_f32_e32 v41, v51, v51
	v_fmac_f32_e32 v41, v50, v50
	v_add_f32_e32 v42, v41, v40
	v_pk_add_f32 v[40:41], v[34:35], v[98:99]
	v_pk_add_f32 v[34:35], v[32:33], v[96:97]
	v_mul_f32_e32 v33, v37, v37
	v_cvt_pk_bf16_f32 v32, v36, v37
	v_fmac_f32_e32 v33, v36, v36
	v_mul_f32_e32 v36, v39, v39
	v_fmac_f32_e32 v36, v38, v38
	v_add_f32_e32 v33, v33, v36
	v_mul_f32_e32 v36, v35, v35
	v_fmac_f32_e32 v36, v34, v34
	v_add_f32_e32 v33, v33, v36
	v_mul_f32_e32 v36, v41, v41
	v_fmac_f32_e32 v36, v40, v40
	v_add_f32_e32 v33, v36, v33
	v_add_f32_e32 v36, v42, v33
	ds_swizzle_b32 v37, v36 offset:swizzle(SWAP,16)
	v_cvt_pk_bf16_f32 v33, v38, v39
	v_cvt_pk_bf16_f32 v34, v34, v35
	v_cvt_pk_bf16_f32 v35, v40, v41
	flat_store_dwordx4 v[48:49], v[32:35] offset:64
	s_waitcnt lgkmcnt(0)
	s_nop 0
	v_add_f32_e32 v32, v36, v37
	v_mov_b32_e32 v33, v32
	s_nop 1
	v_permlane32_swap_b32_e32 v32, v33
	s_and_saveexec_b64 s[20:21], vcc
	s_cbranch_execz .LBB0_737
	v_add_f32_e32 v32, v32, v33
	flat_atomic_add_f32 v[112:113], v32 offset:576

; template <class Epi, bool ALIGN_EPI>
; __device__ __forceinline__ void gemm_phase(LAS unsigned char* lds, const Gemm g, const StaticOrder& S, const Epi& E, const int wid) {
;     int lane = lane_id(); asm volatile("" : "+v"(lane));
;     const int tid = wid * 64 + lane, wr = wid >> 2, wc = wid & 3, fr = lane & 15, fq = lane >> 4;
;     const int K = g.K, nt = K / BK;
;     unsigned voffA[2], voffB[2];
; #pragma unroll
;     for (int i = 0; i < 2; ++i) { int R, C; stage_rc(tid * 16 + i * 8192, R, C); const int Rb = 64 * (R >> 5) + perm32(R & 31);
;         voffA[i] = (unsigned)(R * K + C) * 2u; voffB[i] = (unsigned)(Rb * K + C) * 2u; }
;     const size_t kstep = (size_t)(BK * 2);
;     const size_t hstep = (size_t)HALF * K * 2;
;     const size_t hstepB = (size_t)32 * K * 2;
;     const size_t tstep = 2 * hstep;
;     const unsigned ldsw = (unsigned)wid * 1024u;
;     const int aoff = lds_byte(wr * 64 + fr, fq * 8), boff = lds_byte(wc * 32 + fr, fq * 8);
;     ...
;     Unit cur, nxt; int ui = 0;
;     if (!S.next(0, cur)) return;
;     f32x4 acc[2][2][4][2];
; #pragma unroll
;     for (int a = 0; a < 2; ++a)
; #pragma unroll
;         for (int b = 0; b < 2; ++b)
; #pragma unroll
;             for (int m = 0; m < 4; ++m)
; #pragma unroll
;                 for (int n = 0; n < 2; ++n) acc[a][b][m][n] = (f32x4){0.f, 0.f, 0.f, 0.f};
;     bf16x8 At[4][2], B0[2][2], B1[2][2];
;     const char* cA = (const char*)g.A + (size_t)cur.pm * tstep; const char* cB = (const char*)g.Bt + (size_t)cur.pn * tstep;
;     PG8_STAGE(PG8_SB(0, 0), cB, voffB); PG8_STAGE(PG8_SB(0, 1), cB + hstepB, voffB); PG8_STAGE(PG8_SA(0, 0), cA, voffA); PG8_STAGE(PG8_SA(0, 1), cA + hstep, voffA);
;     if (wr == 1) PG8_BAR;
;     PG8_WAIT_V(2); PG8_BAR;
;     PG8_STAGE(PG8_SB(1, 0), cB + kstep, voffB); PG8_STAGE(PG8_SA(1, 0), cA + kstep, voffA); PG8_STAGE(PG8_SB(1, 1), cB + hstepB + kstep, voffB);
; __global__ void __launch_bounds__(NWAVES * 64, 2) fwd(Args args) {
;     ...
;     if (IN(4)) {
;         unsigned char* wsp = ws; asm volatile("" : "+s"(wsp)); const unsigned char* tbl = wsp + WS_PTRS;
;         float* out = (float*)ld_uptr(tbl, 16);
;         bf16_t* HB = (bf16_t*)(wsp + WS_HB); bf16_t* WgT = (bf16_t*)(wsp + WS_WG); bf16_t* PP = (bf16_t*)(wsp + WS_PP); float* rowss = (float*)(wsp + WS_ROWSS);
;         pg8::Gemm g{HB, WgT, M, DM, DM}; pg8::StaticOrder S; S.init(M, DM, G, bx);
.LBB0_797:
	s_cmp_lt_i32 s82, 5
	s_cselect_b64 s[2:3], -1, 0
	s_and_b64 s[0:1], s[2:3], s[0:1]
	s_andn2_b64 vcc, exec, s[0:1]
	s_cbranch_vccnz .LBB0_818
	v_mov_b32_e32 v0, 0x20000
	global_load_dwordx2 v[120:121], v0, s[80:81] offset:128
	v_mbcnt_lo_u32_b32 v0, -1, 0
	v_mbcnt_hi_u32_b32 v200, -1, v0
	s_cmpk_gt_u32 s77, 0xff
	v_mov_b32_e32 v0, v200
	s_cbranch_scc1 .LBB0_818
	v_lshlrev_b32_e32 v1, 4, v0
	v_add_u32_e32 v2, s33, v1
	v_add_u32_e32 v3, 0x2000, v2
	v_ashrrev_i32_e32 v4, 31, v3
	v_lshrrev_b32_e32 v4, 22, v4
	v_add_u32_e32 v4, v3, v4
	v_ashrrev_i32_e32 v4, 10, v4
	v_mul_i32_i24_e32 v5, 0x400, v4
	v_sub_u32_e32 v3, v3, v5
	v_lshrrev_b32_e32 v5, 4, v3
	v_bitop3_b32 v3, v5, v3, 32 bitop3:0x6c
	v_ashrrev_i32_e32 v5, 31, v3
	v_lshrrev_b32_e32 v5, 26, v5
	v_add_u32_e32 v5, v3, v5
	v_ashrrev_i32_e32 v6, 6, v5
	v_and_b32_e32 v5, 0xffc0, v5
	v_sub_u32_e32 v3, v3, v5
	v_lshlrev_b32_e32 v7, 3, v4
	v_lshrrev_b16_e32 v5, 7, v3
	v_and_b32_e32 v7, -16, v7
	v_and_b32_e32 v5, 1, v5
	v_add_u32_e32 v7, v6, v7
	v_add_u16_e32 v3, v3, v5
	v_mov_b32_e32 v5, 1
	v_lshrrev_b32_e32 v8, 2, v7
	v_lshlrev_b32_e32 v9, 1, v7
	v_lshlrev_b32_e32 v4, 5, v4
	v_ashrrev_i16_sdwa v3, v5, sext(v3) dst_sel:DWORD dst_unused:UNUSED_PAD src0_sel:DWORD src1_sel:BYTE_0
	v_and_b32_e32 v8, 4, v8
	v_and_b32_e32 v6, 3, v6
	v_and_b32_e32 v9, 0xfffd8, v9
	v_and_b32_e32 v4, 32, v4
	v_bfe_i32 v3, v3, 0, 16
	v_or3_b32 v6, v6, v8, v9
	v_add_lshl_u32 v3, v4, v3, 1
	v_lshl_add_u32 v176, v6, 12, v3
	v_lshl_add_u32 v178, v7, 12, v3
	v_ashrrev_i32_e32 v3, 31, v2
	v_lshrrev_b32_e32 v3, 22, v3
	v_add_u32_e32 v3, v2, v3
	v_ashrrev_i32_e32 v3, 10, v3
	v_mul_i32_i24_e32 v4, 0x400, v3
	v_sub_u32_e32 v2, v2, v4
	s_add_u32 s6, s80, 0x5300000
	v_lshrrev_b32_e32 v4, 4, v2
	s_addc_u32 s7, s81, 0
	v_bitop3_b32 v2, v4, v2, 32 bitop3:0x6c
	s_add_u32 s26, s80, 0x2600000
	v_ashrrev_i32_e32 v4, 31, v2
	s_addc_u32 s27, s81, 0
	v_lshrrev_b32_e32 v4, 26, v4
	s_lshl_b32 s1, s77, 5
	v_add_u32_e32 v4, v2, v4
	v_lshlrev_b32_e32 v7, 3, v3
	s_lshr_b32 s0, s77, 3
	s_lshl_b32 s4, s77, 2
	s_and_b32 s1, s1, 32
	v_ashrrev_i32_e32 v6, 6, v4
	v_and_b32_e32 v7, -16, v7
	v_and_b32_e32 v4, 0xc0, v4
	s_and_b32 s4, s4, 24
	s_or_b32 s0, s1, s0
	s_bfe_u32 s1, s77, 0x30003
	v_add_u32_e32 v7, v6, v7
	v_sub_u32_e32 v2, v2, v4
	s_or_b32 s41, s4, s1
	s_bfe_u32 s4, s0, 0x50003
	v_lshrrev_b32_e32 v8, 2, v7
	v_lshlrev_b32_e32 v9, 1, v7
	v_lshlrev_b32_e32 v3, 5, v3
	v_ashrrev_i16_sdwa v2, v5, sext(v2) dst_sel:DWORD dst_unused:UNUSED_PAD src0_sel:DWORD src1_sel:BYTE_0
	s_lshl_b32 s5, s41, 20
	s_lshl_b32 s0, s4, 20
	v_and_b32_e32 v8, 4, v8
	v_and_b32_e32 v6, 3, v6
	v_and_b32_e32 v9, 0xfffd8, v9
	v_and_b32_e32 v3, 32, v3
	v_bfe_i32 v2, v2, 0, 16
	s_add_u32 s18, s26, s0
	v_or3_b32 v6, v6, v8, v9
	v_add_lshl_u32 v2, v3, v2, 1
	s_addc_u32 s19, s27, 0
	s_add_i32 s28, s33, 0
	v_lshl_add_u32 v180, v6, 12, v2
	s_mov_b64 s[0:1], s[18:19]
	s_add_i32 m0, s28, 0x10000
	v_lshl_add_u32 v182, v7, 12, v2
	global_load_lds_dwordx4 v180, s[0:1]
	s_add_i32 m0, s28, 0x12000
	v_mov_b32_e32 v181, 0
	global_load_lds_dwordx4 v176, s[0:1]
	s_add_u32 s0, s18, 0x20000
	s_addc_u32 s1, s19, 0
	s_add_i32 m0, s28, 0x14000
	v_cndmask_b32_e64 v2, 0, 1, s[96:97]
	global_load_lds_dwordx4 v180, s[0:1]
	s_add_i32 m0, s28, 0x16000
	s_add_u32 s20, s6, s5
	s_addc_u32 s21, s7, 0
	global_load_lds_dwordx4 v176, s[0:1]
	s_mov_b64 s[0:1], s[20:21]
	s_mov_b32 m0, s28
	s_add_i32 s29, s28, 0x2000
	v_mov_b32_e32 v177, v181
	global_load_lds_dwordx4 v182, s[0:1]
	s_mov_b32 m0, s29
	v_mov_b32_e32 v183, v181
	global_load_lds_dwordx4 v178, s[0:1]
	s_add_u32 s0, s20, 0x80000
	s_addc_u32 s1, s21, 0
	s_add_i32 s30, s28, 0x4000
	s_mov_b32 m0, s30
	s_add_i32 s31, s28, 0x6000
	s_andn2_b64 vcc, exec, s[96:97]
	global_load_lds_dwordx4 v182, s[0:1]
	s_mov_b32 m0, s31
	v_mov_b32_e32 v179, v181
	global_load_lds_dwordx4 v178, s[0:1]
	v_cmp_ne_u32_e64 s[0:1], 1, v2
	s_cbranch_vccnz .LBB0_801
	s_barrier
.LBB0_801:
	s_and_b32 s42, 0xffff, s4
	s_add_u32 s8, s80, 0xc300000
	s_addc_u32 s9, s81, 0
	s_add_u32 s4, s18, 0x80
	s_addc_u32 s5, s19, 0
	s_waitcnt vmcnt(2)
	v_readfirstlane_b32 s3, v121
	v_readfirstlane_b32 s2, v120
	s_barrier
	s_add_i32 m0, s28, 0x18000
	v_lshl_add_u64 v[2:3], s[4:5], 0, v[180:181]
	global_load_lds_dwordx4 v[2:3], off
	s_add_i32 m0, s28, 0x1a000
	v_lshl_add_u64 v[2:3], s[4:5], 0, v[176:177]
	s_add_u32 s4, s20, 0x80
	s_addc_u32 s5, s21, 0
	s_add_i32 s34, s28, 0x8000
	global_load_lds_dwordx4 v[2:3], off
	s_mov_b32 m0, s34
	v_lshl_add_u64 v[2:3], s[4:5], 0, v[182:183]
	s_add_i32 s35, s28, 0xa000
	global_load_lds_dwordx4 v[2:3], off
	v_lshl_add_u64 v[2:3], s[4:5], 0, v[178:179]
	s_add_u32 s4, s18, 0x20080
	s_mov_b32 m0, s35
	s_addc_u32 s5, s19, 0
	global_load_lds_dwordx4 v[2:3], off
	s_add_i32 m0, s28, 0x1c000
	v_lshl_add_u64 v[2:3], s[4:5], 0, v[180:181]
	global_load_lds_dwordx4 v[2:3], off
	v_lshl_add_u64 v[2:3], s[4:5], 0, v[176:177]
	s_add_i32 m0, s28, 0x1e000
	v_and_b32_e32 v5, 48, v0
	global_load_lds_dwordx4 v[2:3], off
	v_and_b32_e32 v2, 15, v0
	v_or_b32_e32 v3, s79, v2
	v_lshlrev_b32_e32 v4, 6, v3
	s_movk_i32 s4, 0x3c0
	v_and_b32_e32 v1, 0xfffffc00, v1
	v_lshlrev_b32_e32 v3, 2, v3
	v_lshlrev_b32_e32 v0, 2, v0
	v_and_or_b32 v4, v4, s4, v5
	v_add_u32_e32 v6, s94, v1
	v_and_b32_e32 v3, 32, v3
	v_lshl_or_b32 v2, v2, 6, v5
	v_add_u32_e32 v1, s93, v1
	v_and_b32_e32 v0, 32, v0
	s_waitcnt vmcnt(6)
	v_bitop3_b32 v3, v4, v6, v3 bitop3:0xde
	v_bitop3_b32 v201, v2, v1, v0 bitop3:0xde
	s_add_i32 s38, 0, 0x10000
	s_add_i32 s39, 0, 0x14000
	s_mov_b32 s36, 0
	s_ashr_i32 s37, s78, 31
	v_mov_b64_e32 v[184:185], 0x100
	v_mov_b64_e32 v[186:187], 0xff
	v_add_u32_e32 v202, s38, v201
	v_add_u32_e32 v203, s39, v201
	v_add_u32_e32 v204, 0, v3
	v_mov_b32_e32 v205, 0x358637bd
	s_mov_b32 s40, 0x800000
	s_barrier
	s_branch .LBB0_804

;     __device__ __forceinline__ void operator()(const Acc& acc, const Unit& u, int wr, int wc, int fr, int fq) const {
;         asm volatile("" : "+v"(fr), "+v"(fq));
;         const int colbase = u.pn * 256 + wc * 64 + 8 * fq;
; #pragma unroll
;         for (int ai = 0; ai < 2; ++ai) {
;             f32x4 hv[4][2][2]; u32x4 pw[4][2]; float rsv[4];
; #pragma unroll
;             for (int m = 0; m < 4; ++m) { const int row = u.pm * 256 + ai * 128 + wr * 64 + m * 16 + fr; const size_t off = (size_t)row * DM + colbase;
;                 rsv[m] = rowss[row];
; #pragma unroll
;                 for (int bj = 0; bj < 2; ++bj) { const u32x4 hw = __builtin_nontemporal_load((const u32x4*)(hin + off + 32 * bj));
;                     hv[m][bj][0] = (f32x4){bflo(hw.x), bfhi(hw.x), bflo(hw.y), bfhi(hw.y)}; hv[m][bj][1] = (f32x4){bflo(hw.z), bfhi(hw.z), bflo(hw.w), bfhi(hw.w)};
;                     pw[m][bj] = __builtin_nontemporal_load((const u32x4*)(PP + off + 32 * bj)); } }
; #pragma unroll
;             for (int m = 0; m < 4; ++m) {
;                 const int row = u.pm * 256 + ai * 128 + wr * 64 + m * 16 + fr;
;                 const float rs = rsqrtf(rsv[m] * (1.0f / DM) + EPS) * -1.4426950408889634f;
; #pragma unroll
;                 for (int bj = 0; bj < 2; ++bj) {
;                     const size_t off = (size_t)row * DM + colbase + 32 * bj;
;                     f32x4 h0 = hv[m][bj][0], h1 = hv[m][bj][1];
;                     const u32x4 p4 = pw[m][bj];
;                     const f32x4 a0 = acc[ai][bj][m][0], a1 = acc[ai][bj][m][1];
;                     h0.x += bflo(p4.x) * __builtin_amdgcn_rcpf(1.0f + __builtin_amdgcn_exp2f(a0.x * rs));
;                     h0.y += bfhi(p4.x) * __builtin_amdgcn_rcpf(1.0f + __builtin_amdgcn_exp2f(a0.y * rs));
;                     h0.z += bflo(p4.y) * __builtin_amdgcn_rcpf(1.0f + __builtin_amdgcn_exp2f(a0.z * rs));
;                     h0.w += bfhi(p4.y) * __builtin_amdgcn_rcpf(1.0f + __builtin_amdgcn_exp2f(a0.w * rs));
;                     h1.x += bflo(p4.z) * __builtin_amdgcn_rcpf(1.0f + __builtin_amdgcn_exp2f(a1.x * rs));
;                     h1.y += bfhi(p4.z) * __builtin_amdgcn_rcpf(1.0f + __builtin_amdgcn_exp2f(a1.y * rs));
;                     h1.z += bflo(p4.w) * __builtin_amdgcn_rcpf(1.0f + __builtin_amdgcn_exp2f(a1.z * rs));
.LBB0_814:
	v_mov_b64_e32 v[206:207], v[224:225]
	v_mov_b64_e32 v[208:209], v[226:227]
	v_mov_b64_e32 v[172:173], v[228:229]
	v_mov_b64_e32 v[174:175], v[230:231]
	v_mov_b64_e32 v[164:165], v[232:233]
	v_mov_b64_e32 v[166:167], v[234:235]
	v_mov_b64_e32 v[156:157], v[236:237]
	v_mov_b64_e32 v[158:159], v[238:239]
	v_mov_b64_e32 v[148:149], v[240:241]
	v_mov_b64_e32 v[150:151], v[242:243]
	v_mov_b64_e32 v[140:141], v[210:211]
	v_mov_b64_e32 v[142:143], v[212:213]
	v_mov_b64_e32 v[236:237], v[218:219]
	v_mov_b64_e32 v[238:239], v[220:221]
	v_mov_b64_e32 v[240:241], v[222:223]
	v_mov_b32_e32 v128, v200
	s_lshl_b32 s11, s42, 8
	v_and_b32_e32 v129, 15, v128
	v_bfe_u32 v128, v128, 4, 2
	s_or_b32 s11, s11, s86
	s_nop 0
	v_lshl_add_u32 v188, v128, 3, s11
	s_lshl_b32 s11, s41, 8
	s_add_i32 s11, s11, s79
	v_add_u32_e32 v190, s11, v129
	v_ashrrev_i32_e32 v191, 31, v190
	v_lshl_add_u64 v[192:193], v[190:191], 2, s[80:81]
	flat_load_dword v226, v[192:193]
	v_ashrrev_i32_e32 v189, 31, v188
	v_lshlrev_b64 v[128:129], 11, v[190:191]
	v_lshl_add_u64 v[222:223], v[128:129], 0, v[188:189]
	v_lshlrev_b64 v[128:129], 1, v[222:223]
	v_lshl_add_u64 v[130:131], s[6:7], 0, v[128:129]
	v_lshl_add_u64 v[128:129], s[8:9], 0, v[128:129]
	flat_load_dwordx4 v[210:213], v[128:129] nt
	flat_load_dword v234, v[192:193] offset:64
	flat_load_dword v235, v[192:193] offset:128
	flat_load_dword v191, v[192:193] offset:192
	flat_load_dwordx4 v[218:221], v[128:129] offset:64 nt
	v_add_u32_e32 v132, 16, v190
	v_add_u32_e32 v134, 32, v190
	v_add_u32_e32 v136, 48, v190
	v_ashrrev_i32_e32 v133, 31, v132
	v_ashrrev_i32_e32 v135, 31, v134
	v_ashrrev_i32_e32 v137, 31, v136
	v_lshlrev_b64 v[132:133], 11, v[132:133]
	v_lshlrev_b64 v[134:135], 11, v[134:135]
	v_lshlrev_b64 v[136:137], 11, v[136:137]
	v_lshl_add_u64 v[198:199], v[132:133], 0, v[188:189]
	v_lshl_add_u64 v[196:197], v[134:135], 0, v[188:189]
	v_lshl_add_u64 v[194:195], v[136:137], 0, v[188:189]
	v_lshlrev_b64 v[132:133], 1, v[198:199]
	v_lshlrev_b64 v[134:135], 1, v[196:197]
	v_lshlrev_b64 v[136:137], 1, v[194:195]
	v_lshl_add_u64 v[128:129], s[6:7], 0, v[132:133]
	v_lshl_add_u64 v[130:131], s[8:9], 0, v[132:133]
	v_lshl_add_u64 v[132:133], s[6:7], 0, v[134:135]
	v_lshl_add_u64 v[134:135], s[8:9], 0, v[134:135]
	v_lshl_add_u64 v[138:139], s[6:7], 0, v[136:137]
	v_lshl_add_u64 v[224:225], s[8:9], 0, v[136:137]
	flat_load_dwordx4 v[168:171], v[130:131] nt
	flat_load_dwordx4 v[160:163], v[130:131] offset:64 nt
	flat_load_dwordx4 v[152:155], v[134:135] nt
	flat_load_dwordx4 v[144:147], v[134:135] offset:64 nt
	s_nop 0
	v_mov_b64_e32 v[132:133], v[244:245]
	v_mov_b64_e32 v[134:135], v[246:247]
	s_nop 0
	flat_load_dwordx4 v[136:139], v[224:225] nt
	flat_load_dwordx4 v[128:131], v[224:225] offset:64 nt
	s_waitcnt vmcnt(0) lgkmcnt(0)
	v_fmamk_f32 v224, v226, 0x3a000000, v205
	v_mul_f32_e32 v225, 0x4b800000, v224
	v_cmp_gt_f32_e32 vcc, s40, v224
	v_lshlrev_b32_e32 v228, 16, v208
	s_nop 0
	v_cndmask_b32_e32 v224, v224, v225, vcc
	v_rsq_f32_e32 v232, v224
	v_and_b32_e32 v229, 0xffff0000, v208
	v_lshlrev_b32_e32 v230, 16, v212
	v_and_b32_e32 v231, 0xffff0000, v212
	v_mul_f32_e32 v208, 0x45800000, v232
	v_cndmask_b32_e32 v208, v232, v208, vcc
	v_mul_f32_e32 v212, 0xbfb8aa3b, v208
	v_mul_f32_e32 v124, v124, v212
	v_mul_f32_e32 v125, v125, v212
	v_mul_f32_e32 v120, v120, v212
	v_mul_f32_e32 v121, v121, v212
	v_exp_f32_e32 v124, v124
	v_exp_f32_e32 v125, v125
	v_exp_f32_e32 v120, v120
	v_exp_f32_e32 v121, v121
	v_add_f32_e32 v124, 1.0, v124
	v_add_f32_e32 v125, 1.0, v125
	v_add_f32_e32 v208, 1.0, v120
	v_add_f32_e32 v233, 1.0, v121
	v_rcp_f32_e32 v120, v124
	v_rcp_f32_e32 v121, v125
	v_lshlrev_b32_e32 v224, 16, v206
	v_and_b32_e32 v225, 0xffff0000, v206
	v_lshlrev_b32_e32 v226, 16, v210
	v_and_b32_e32 v227, 0xffff0000, v210
	v_mul_f32_e32 v126, v126, v212
	v_mul_f32_e32 v127, v127, v212
	v_mul_f32_e32 v122, v122, v212
	v_exp_f32_e32 v126, v126
	v_exp_f32_e32 v127, v127
	v_pk_fma_f32 v[124:125], v[120:121], v[226:227], v[224:225]
	v_mul_f32_e32 v120, v123, v212
	v_exp_f32_e32 v122, v122
	v_exp_f32_e32 v123, v120
	v_mul_f32_e32 v116, v116, v212
	v_mul_f32_e32 v117, v117, v212
	v_exp_f32_e32 v116, v116
	v_exp_f32_e32 v117, v117
	v_mul_f32_e32 v118, v118, v212
	v_mul_f32_e32 v119, v119, v212
	v_add_f32_e32 v126, 1.0, v126
	v_add_f32_e32 v127, 1.0, v127
	v_exp_f32_e32 v118, v118
	v_exp_f32_e32 v119, v119
	v_mul_f32_e32 v112, v112, v212
	v_mul_f32_e32 v113, v113, v212
	v_rcp_f32_e32 v126, v126
	v_rcp_f32_e32 v127, v127
	v_add_f32_e32 v122, 1.0, v122
	v_add_f32_e32 v123, 1.0, v123
	v_exp_f32_e32 v112, v112
	v_exp_f32_e32 v113, v113
	v_rcp_f32_e32 v232, v208
	v_rcp_f32_e32 v233, v233
	v_rcp_f32_e32 v122, v122
	v_rcp_f32_e32 v123, v123
	v_add_f32_e32 v116, 1.0, v116
	v_add_f32_e32 v117, 1.0, v117
	v_lshlrev_b32_e32 v206, 16, v207
	v_and_b32_e32 v207, 0xffff0000, v207
	v_lshlrev_b32_e32 v210, 16, v211
	v_and_b32_e32 v211, 0xffff0000, v211
	v_rcp_f32_e32 v116, v116
	v_rcp_f32_e32 v117, v117
	v_add_f32_e32 v118, 1.0, v118
	v_add_f32_e32 v119, 1.0, v119
	v_pk_fma_f32 v[126:127], v[126:127], v[210:211], v[206:207]
	v_lshlrev_b32_e32 v206, 16, v209
	v_and_b32_e32 v207, 0xffff0000, v209
	v_lshlrev_b32_e32 v208, 16, v213
	v_and_b32_e32 v209, 0xffff0000, v213
	v_rcp_f32_e32 v118, v118
	v_rcp_f32_e32 v119, v119
	v_add_f32_e32 v112, 1.0, v112
	v_add_f32_e32 v113, 1.0, v113
	v_pk_fma_f32 v[120:121], v[232:233], v[230:231], v[228:229]
	v_pk_fma_f32 v[122:123], v[122:123], v[208:209], v[206:207]
	v_lshl_add_u64 v[206:207], v[222:223], 2, s[2:3]
	v_rcp_f32_e32 v112, v112
	v_rcp_f32_e32 v113, v113
	flat_store_dwordx4 v[206:207], v[120:123] offset:16
; __device__ __forceinline__ float bflo(unsigned u) { return __uint_as_float(u << 16); }
; __device__ __forceinline__ float bfhi(unsigned u) { return __uint_as_float(u & 0xffff0000u); }
;     __device__ __forceinline__ void operator()(const Acc& acc, const Unit& u, int wr, int wc, int fr, int fq) const {
;     ...
;             for (int m = 0; m < 4; ++m) {
;                 const int row = u.pm * 256 + ai * 128 + wr * 64 + m * 16 + fr;
;                 const float rs = rsqrtf(rsv[m] * (1.0f / DM) + EPS) * -1.4426950408889634f;
; #pragma unroll
;                 for (int bj = 0; bj < 2; ++bj) {
;                     const size_t off = (size_t)row * DM + colbase + 32 * bj;
;                     f32x4 h0 = hv[m][bj][0], h1 = hv[m][bj][1];
;                     const u32x4 p4 = pw[m][bj];
;                     const f32x4 a0 = acc[ai][bj][m][0], a1 = acc[ai][bj][m][1];
;                     h0.x += bflo(p4.x) * __builtin_amdgcn_rcpf(1.0f + __builtin_amdgcn_exp2f(a0.x * rs));
;                     h0.y += bfhi(p4.x) * __builtin_amdgcn_rcpf(1.0f + __builtin_amdgcn_exp2f(a0.y * rs));
;                     h0.z += bflo(p4.y) * __builtin_amdgcn_rcpf(1.0f + __builtin_amdgcn_exp2f(a0.z * rs));
;                     h0.w += bfhi(p4.y) * __builtin_amdgcn_rcpf(1.0f + __builtin_amdgcn_exp2f(a0.w * rs));
;                     h1.x += bflo(p4.z) * __builtin_amdgcn_rcpf(1.0f + __builtin_amdgcn_exp2f(a1.x * rs));
;                     h1.y += bfhi(p4.z) * __builtin_amdgcn_rcpf(1.0f + __builtin_amdgcn_exp2f(a1.y * rs));
;                     h1.z += bflo(p4.w) * __builtin_amdgcn_rcpf(1.0f + __builtin_amdgcn_exp2f(a1.z * rs));
;                     h1.w += bfhi(p4.w) * __builtin_amdgcn_rcpf(1.0f + __builtin_amdgcn_exp2f(a1.w * rs));
;                     *(f32x4*)(out + off) = h0; *(f32x4*)(out + off + 4) = h1;
	flat_store_dwordx4 v[206:207], v[124:127]
	v_mul_f32_e32 v114, v114, v212
	v_lshlrev_b32_e32 v120, 16, v214
	v_and_b32_e32 v121, 0xffff0000, v214
	v_lshlrev_b32_e32 v122, 16, v218
	v_and_b32_e32 v123, 0xffff0000, v218
	v_pk_fma_f32 v[116:117], v[116:117], v[122:123], v[120:121]
	v_lshlrev_b32_e32 v120, 16, v215
	v_and_b32_e32 v121, 0xffff0000, v215
	v_lshlrev_b32_e32 v122, 16, v219
	v_and_b32_e32 v123, 0xffff0000, v219
	v_pk_fma_f32 v[118:119], v[118:119], v[122:123], v[120:121]
	v_lshlrev_b32_e32 v120, 16, v216
	v_and_b32_e32 v121, 0xffff0000, v216
	v_lshlrev_b32_e32 v122, 16, v220
	v_and_b32_e32 v123, 0xffff0000, v220
	v_pk_fma_f32 v[112:113], v[112:113], v[122:123], v[120:121]
	v_fmamk_f32 v123, v234, 0x3a000000, v205
	v_mul_f32_e32 v124, 0x4b800000, v123
	v_cmp_gt_f32_e32 vcc, s40, v123
	flat_store_dwordx4 v[206:207], v[116:119] offset:128
	v_mul_f32_e32 v115, v115, v212
	v_cndmask_b32_e32 v123, v123, v124, vcc
	v_rsq_f32_e32 v124, v123
	v_exp_f32_e32 v114, v114
	v_exp_f32_e32 v115, v115
	v_lshlrev_b32_e32 v120, 16, v217
	v_mul_f32_e32 v116, 0x45800000, v124
	v_cndmask_b32_e32 v116, v124, v116, vcc
	v_mul_f32_e32 v116, 0xbfb8aa3b, v116
	v_mul_f32_e32 v108, v108, v116
	v_mul_f32_e32 v109, v109, v116
	v_exp_f32_e32 v108, v108
	v_exp_f32_e32 v109, v109
	v_mul_f32_e32 v110, v110, v116
	v_mul_f32_e32 v111, v111, v116
	v_exp_f32_e32 v110, v110
	v_exp_f32_e32 v111, v111
	v_mul_f32_e32 v104, v104, v116
	v_mul_f32_e32 v105, v105, v116
	v_add_f32_e32 v114, 1.0, v114
	v_add_f32_e32 v115, 1.0, v115
	v_exp_f32_e32 v104, v104
	v_exp_f32_e32 v105, v105
	v_mul_f32_e32 v106, v106, v116
	v_mul_f32_e32 v107, v107, v116
	v_rcp_f32_e32 v114, v114
	v_rcp_f32_e32 v115, v115
	v_exp_f32_e32 v106, v106
	v_exp_f32_e32 v107, v107
	v_add_f32_e32 v108, 1.0, v108
	v_add_f32_e32 v109, 1.0, v109
	v_mul_f32_e32 v100, v100, v116
	v_mul_f32_e32 v101, v101, v116
	v_rcp_f32_e32 v108, v108
	v_rcp_f32_e32 v109, v109
	v_add_f32_e32 v110, 1.0, v110
	v_add_f32_e32 v111, 1.0, v111
	v_exp_f32_e32 v100, v100
	v_exp_f32_e32 v101, v101
	v_mul_f32_e32 v102, v102, v116
	v_mul_f32_e32 v103, v103, v116
	v_and_b32_e32 v121, 0xffff0000, v217
	v_lshlrev_b32_e32 v122, 16, v221
	v_and_b32_e32 v123, 0xffff0000, v221
	v_rcp_f32_e32 v110, v110
	v_rcp_f32_e32 v111, v111
	v_add_f32_e32 v104, 1.0, v104
	v_add_f32_e32 v105, 1.0, v105
	v_exp_f32_e32 v102, v102
	v_exp_f32_e32 v103, v103
	v_mul_f32_e32 v96, v96, v116
	v_mul_f32_e32 v97, v97, v116
	v_pk_fma_f32 v[114:115], v[114:115], v[122:123], v[120:121]
	v_rcp_f32_e32 v104, v104
	v_rcp_f32_e32 v105, v105
	v_add_f32_e32 v106, 1.0, v106
	v_add_f32_e32 v107, 1.0, v107
	v_exp_f32_e32 v96, v96
	v_exp_f32_e32 v97, v97
	flat_store_dwordx4 v[206:207], v[112:115] offset:144
	v_rcp_f32_e32 v106, v106
	v_rcp_f32_e32 v107, v107
	v_lshlrev_b32_e32 v112, 16, v172
	v_and_b32_e32 v113, 0xffff0000, v172
	v_lshlrev_b32_e32 v114, 16, v168
	v_and_b32_e32 v115, 0xffff0000, v168
	v_pk_fma_f32 v[108:109], v[108:109], v[114:115], v[112:113]
	v_lshlrev_b32_e32 v112, 16, v173
	v_and_b32_e32 v113, 0xffff0000, v173
	v_lshlrev_b32_e32 v114, 16, v169
	v_and_b32_e32 v115, 0xffff0000, v169
	v_add_f32_e32 v100, 1.0, v100
	v_add_f32_e32 v101, 1.0, v101
	v_pk_fma_f32 v[110:111], v[110:111], v[114:115], v[112:113]
	v_lshlrev_b32_e32 v112, 16, v174
	v_and_b32_e32 v113, 0xffff0000, v174
	v_lshlrev_b32_e32 v114, 16, v170
	v_and_b32_e32 v115, 0xffff0000, v170
	v_rcp_f32_e32 v100, v100
	v_rcp_f32_e32 v101, v101
	v_add_f32_e32 v102, 1.0, v102
	v_add_f32_e32 v103, 1.0, v103
	v_pk_fma_f32 v[104:105], v[104:105], v[114:115], v[112:113]
	v_lshlrev_b32_e32 v112, 16, v175
	v_and_b32_e32 v113, 0xffff0000, v175
	v_lshlrev_b32_e32 v114, 16, v171
	v_and_b32_e32 v115, 0xffff0000, v171
	v_rcp_f32_e32 v102, v102
	v_rcp_f32_e32 v103, v103
	v_add_f32_e32 v96, 1.0, v96
	v_add_f32_e32 v97, 1.0, v97
	v_pk_fma_f32 v[106:107], v[106:107], v[114:115], v[112:113]
	v_lshl_add_u64 v[112:113], v[198:199], 2, s[2:3]
	v_rcp_f32_e32 v96, v96
	v_rcp_f32_e32 v97, v97
	flat_store_dwordx4 v[112:113], v[104:107] offset:16
	flat_store_dwordx4 v[112:113], v[108:111]
	v_mul_f32_e32 v98, v98, v116
	v_lshlrev_b32_e32 v104, 16, v164
	v_and_b32_e32 v105, 0xffff0000, v164
	v_lshlrev_b32_e32 v106, 16, v160
	v_and_b32_e32 v107, 0xffff0000, v160
	v_pk_fma_f32 v[100:101], v[100:101], v[106:107], v[104:105]
	v_lshlrev_b32_e32 v104, 16, v165
	v_and_b32_e32 v105, 0xffff0000, v165
	v_lshlrev_b32_e32 v106, 16, v161
	v_and_b32_e32 v107, 0xffff0000, v161
	v_pk_fma_f32 v[102:103], v[102:103], v[106:107], v[104:105]
	v_lshlrev_b32_e32 v104, 16, v166
	v_and_b32_e32 v105, 0xffff0000, v166
	v_lshlrev_b32_e32 v106, 16, v162
	v_and_b32_e32 v107, 0xffff0000, v162
	v_pk_fma_f32 v[96:97], v[96:97], v[106:107], v[104:105]
	v_fmamk_f32 v107, v235, 0x3a000000, v205
	v_mul_f32_e32 v108, 0x4b800000, v107
	v_cmp_gt_f32_e32 vcc, s40, v107
	flat_store_dwordx4 v[112:113], v[100:103] offset:128
	v_mul_f32_e32 v99, v99, v116
	v_cndmask_b32_e32 v107, v107, v108, vcc
	v_rsq_f32_e32 v108, v107
	v_exp_f32_e32 v98, v98
	v_exp_f32_e32 v99, v99
	v_lshlrev_b32_e32 v104, 16, v167
	v_mul_f32_e32 v100, 0x45800000, v108
	v_cndmask_b32_e32 v100, v108, v100, vcc
	v_mul_f32_e32 v100, 0xbfb8aa3b, v100
	v_mul_f32_e32 v92, v92, v100
	v_mul_f32_e32 v93, v93, v100
	v_exp_f32_e32 v92, v92
	v_exp_f32_e32 v93, v93
	v_mul_f32_e32 v94, v94, v100
	v_mul_f32_e32 v95, v95, v100
	v_exp_f32_e32 v94, v94
	v_exp_f32_e32 v95, v95
	v_mul_f32_e32 v88, v88, v100
	v_mul_f32_e32 v89, v89, v100
	v_add_f32_e32 v98, 1.0, v98
	v_add_f32_e32 v99, 1.0, v99
	v_exp_f32_e32 v88, v88
	v_exp_f32_e32 v89, v89
	v_mul_f32_e32 v90, v90, v100
	v_mul_f32_e32 v91, v91, v100
	v_rcp_f32_e32 v98, v98
; __device__ __forceinline__ float bflo(unsigned u) { return __uint_as_float(u << 16); }
; __device__ __forceinline__ float bfhi(unsigned u) { return __uint_as_float(u & 0xffff0000u); }
;     __device__ __forceinline__ void operator()(const Acc& acc, const Unit& u, int wr, int wc, int fr, int fq) const {
;     ...
;             for (int m = 0; m < 4; ++m) {
;                 const int row = u.pm * 256 + ai * 128 + wr * 64 + m * 16 + fr;
;                 const float rs = rsqrtf(rsv[m] * (1.0f / DM) + EPS) * -1.4426950408889634f;
; #pragma unroll
;                 for (int bj = 0; bj < 2; ++bj) {
;                     const size_t off = (size_t)row * DM + colbase + 32 * bj;
;                     f32x4 h0 = hv[m][bj][0], h1 = hv[m][bj][1];
;                     const u32x4 p4 = pw[m][bj];
;                     const f32x4 a0 = acc[ai][bj][m][0], a1 = acc[ai][bj][m][1];
;                     h0.x += bflo(p4.x) * __builtin_amdgcn_rcpf(1.0f + __builtin_amdgcn_exp2f(a0.x * rs));
;                     h0.y += bfhi(p4.x) * __builtin_amdgcn_rcpf(1.0f + __builtin_amdgcn_exp2f(a0.y * rs));
;                     h0.z += bflo(p4.y) * __builtin_amdgcn_rcpf(1.0f + __builtin_amdgcn_exp2f(a0.z * rs));
;                     h0.w += bfhi(p4.y) * __builtin_amdgcn_rcpf(1.0f + __builtin_amdgcn_exp2f(a0.w * rs));
;                     h1.x += bflo(p4.z) * __builtin_amdgcn_rcpf(1.0f + __builtin_amdgcn_exp2f(a1.x * rs));
;                     h1.y += bfhi(p4.z) * __builtin_amdgcn_rcpf(1.0f + __builtin_amdgcn_exp2f(a1.y * rs));
;                     h1.z += bflo(p4.w) * __builtin_amdgcn_rcpf(1.0f + __builtin_amdgcn_exp2f(a1.z * rs));
;                     h1.w += bfhi(p4.w) * __builtin_amdgcn_rcpf(1.0f + __builtin_amdgcn_exp2f(a1.w * rs));
;                     *(f32x4*)(out + off) = h0; *(f32x4*)(out + off + 4) = h1;
	v_rcp_f32_e32 v99, v99
	v_exp_f32_e32 v90, v90
	v_exp_f32_e32 v91, v91
	v_add_f32_e32 v92, 1.0, v92
	v_add_f32_e32 v93, 1.0, v93
	v_mul_f32_e32 v84, v84, v100
	v_mul_f32_e32 v85, v85, v100
	v_rcp_f32_e32 v92, v92
	v_rcp_f32_e32 v93, v93
	v_add_f32_e32 v94, 1.0, v94
	v_add_f32_e32 v95, 1.0, v95
	v_exp_f32_e32 v84, v84
	v_exp_f32_e32 v85, v85
	v_mul_f32_e32 v86, v86, v100
	v_mul_f32_e32 v87, v87, v100
	v_and_b32_e32 v105, 0xffff0000, v167
	v_lshlrev_b32_e32 v106, 16, v163
	v_and_b32_e32 v107, 0xffff0000, v163
	v_rcp_f32_e32 v94, v94
	v_rcp_f32_e32 v95, v95
	v_add_f32_e32 v88, 1.0, v88
	v_add_f32_e32 v89, 1.0, v89
	v_exp_f32_e32 v86, v86
	v_exp_f32_e32 v87, v87
	v_mul_f32_e32 v80, v80, v100
	v_mul_f32_e32 v81, v81, v100
	v_pk_fma_f32 v[98:99], v[98:99], v[106:107], v[104:105]
	v_rcp_f32_e32 v88, v88
	v_rcp_f32_e32 v89, v89
	v_add_f32_e32 v90, 1.0, v90
	v_add_f32_e32 v91, 1.0, v91
	v_exp_f32_e32 v80, v80
	v_exp_f32_e32 v81, v81
	flat_store_dwordx4 v[112:113], v[96:99] offset:144
	v_rcp_f32_e32 v90, v90
	v_rcp_f32_e32 v91, v91
	v_lshlrev_b32_e32 v96, 16, v156
	v_and_b32_e32 v97, 0xffff0000, v156
	v_lshlrev_b32_e32 v98, 16, v152
	v_and_b32_e32 v99, 0xffff0000, v152
	v_pk_fma_f32 v[92:93], v[92:93], v[98:99], v[96:97]
	v_lshlrev_b32_e32 v96, 16, v157
	v_and_b32_e32 v97, 0xffff0000, v157
	v_lshlrev_b32_e32 v98, 16, v153
	v_and_b32_e32 v99, 0xffff0000, v153
	v_add_f32_e32 v84, 1.0, v84
	v_add_f32_e32 v85, 1.0, v85
	v_pk_fma_f32 v[94:95], v[94:95], v[98:99], v[96:97]
	v_lshlrev_b32_e32 v96, 16, v158
	v_and_b32_e32 v97, 0xffff0000, v158
	v_lshlrev_b32_e32 v98, 16, v154
	v_and_b32_e32 v99, 0xffff0000, v154
	v_rcp_f32_e32 v84, v84
	v_rcp_f32_e32 v85, v85
	v_add_f32_e32 v86, 1.0, v86
	v_add_f32_e32 v87, 1.0, v87
	v_pk_fma_f32 v[88:89], v[88:89], v[98:99], v[96:97]
	v_lshlrev_b32_e32 v96, 16, v159
	v_and_b32_e32 v97, 0xffff0000, v159
	v_lshlrev_b32_e32 v98, 16, v155
	v_and_b32_e32 v99, 0xffff0000, v155
	v_rcp_f32_e32 v86, v86
	v_rcp_f32_e32 v87, v87
	v_add_f32_e32 v80, 1.0, v80
	v_add_f32_e32 v81, 1.0, v81
	v_pk_fma_f32 v[90:91], v[90:91], v[98:99], v[96:97]
	v_lshl_add_u64 v[96:97], v[196:197], 2, s[2:3]
	v_rcp_f32_e32 v80, v80
	v_rcp_f32_e32 v81, v81
	flat_store_dwordx4 v[96:97], v[88:91] offset:16
	flat_store_dwordx4 v[96:97], v[92:95]
	v_mul_f32_e32 v82, v82, v100
	v_lshlrev_b32_e32 v88, 16, v148
	v_and_b32_e32 v89, 0xffff0000, v148
	v_lshlrev_b32_e32 v90, 16, v144
	v_and_b32_e32 v91, 0xffff0000, v144
	v_pk_fma_f32 v[84:85], v[84:85], v[90:91], v[88:89]
	v_lshlrev_b32_e32 v88, 16, v149
	v_and_b32_e32 v89, 0xffff0000, v149
	v_lshlrev_b32_e32 v90, 16, v145
	v_and_b32_e32 v91, 0xffff0000, v145
	v_pk_fma_f32 v[86:87], v[86:87], v[90:91], v[88:89]
	v_lshlrev_b32_e32 v88, 16, v150
	v_and_b32_e32 v89, 0xffff0000, v150
	v_lshlrev_b32_e32 v90, 16, v146
	v_and_b32_e32 v91, 0xffff0000, v146
	v_pk_fma_f32 v[80:81], v[80:81], v[90:91], v[88:89]
	v_fmamk_f32 v91, v191, 0x3a000000, v205
	v_mul_f32_e32 v92, 0x4b800000, v91
	v_cmp_gt_f32_e32 vcc, s40, v91
	flat_store_dwordx4 v[96:97], v[84:87] offset:128
	v_mul_f32_e32 v83, v83, v100
	v_cndmask_b32_e32 v91, v91, v92, vcc
	v_rsq_f32_e32 v92, v91
	v_exp_f32_e32 v82, v82
	v_exp_f32_e32 v83, v83
	v_lshlrev_b32_e32 v88, 16, v151
	v_mul_f32_e32 v84, 0x45800000, v92
	v_cndmask_b32_e32 v84, v92, v84, vcc
	v_mul_f32_e32 v84, 0xbfb8aa3b, v84
	v_mul_f32_e32 v76, v76, v84
	v_mul_f32_e32 v77, v77, v84
	v_exp_f32_e32 v76, v76
	v_exp_f32_e32 v77, v77
	v_mul_f32_e32 v78, v78, v84
	v_mul_f32_e32 v79, v79, v84
	v_exp_f32_e32 v78, v78
	v_exp_f32_e32 v79, v79
	v_mul_f32_e32 v72, v72, v84
	v_mul_f32_e32 v73, v73, v84
	v_add_f32_e32 v82, 1.0, v82
	v_add_f32_e32 v83, 1.0, v83
	v_exp_f32_e32 v72, v72
	v_exp_f32_e32 v73, v73
	v_mul_f32_e32 v74, v74, v84
	v_mul_f32_e32 v75, v75, v84
	v_rcp_f32_e32 v82, v82
	v_rcp_f32_e32 v83, v83
	v_exp_f32_e32 v74, v74
	v_exp_f32_e32 v75, v75
	v_add_f32_e32 v76, 1.0, v76
	v_add_f32_e32 v77, 1.0, v77
	v_mul_f32_e32 v68, v68, v84
	v_mul_f32_e32 v69, v69, v84
	v_rcp_f32_e32 v76, v76
	v_rcp_f32_e32 v77, v77
	v_add_f32_e32 v78, 1.0, v78
	v_add_f32_e32 v79, 1.0, v79
	v_exp_f32_e32 v68, v68
	v_exp_f32_e32 v69, v69
	v_mul_f32_e32 v70, v70, v84
	v_mul_f32_e32 v71, v71, v84
	v_and_b32_e32 v89, 0xffff0000, v151
	v_lshlrev_b32_e32 v90, 16, v147
	v_and_b32_e32 v91, 0xffff0000, v147
	v_rcp_f32_e32 v78, v78
	v_rcp_f32_e32 v79, v79
	v_add_f32_e32 v72, 1.0, v72
	v_add_f32_e32 v73, 1.0, v73
	v_exp_f32_e32 v70, v70
	v_exp_f32_e32 v71, v71
	v_mul_f32_e32 v64, v64, v84
	v_mul_f32_e32 v65, v65, v84
	v_pk_fma_f32 v[82:83], v[82:83], v[90:91], v[88:89]
	v_rcp_f32_e32 v72, v72
	v_rcp_f32_e32 v73, v73
	v_add_f32_e32 v74, 1.0, v74
	v_add_f32_e32 v75, 1.0, v75
	v_exp_f32_e32 v64, v64
	v_exp_f32_e32 v65, v65
	v_mul_f32_e32 v66, v66, v84
	v_mul_f32_e32 v67, v67, v84
	flat_store_dwordx4 v[96:97], v[80:83] offset:144
	v_rcp_f32_e32 v74, v74
	v_rcp_f32_e32 v75, v75
	v_lshlrev_b32_e32 v80, 16, v140
	v_and_b32_e32 v81, 0xffff0000, v140
	v_lshlrev_b32_e32 v82, 16, v136
	v_and_b32_e32 v83, 0xffff0000, v136
	v_exp_f32_e32 v66, v66
	v_exp_f32_e32 v67, v67
	v_pk_fma_f32 v[76:77], v[76:77], v[82:83], v[80:81]
	v_lshlrev_b32_e32 v80, 16, v141
	v_and_b32_e32 v81, 0xffff0000, v141
	v_lshlrev_b32_e32 v82, 16, v137
	v_and_b32_e32 v83, 0xffff0000, v137
	v_add_f32_e32 v68, 1.0, v68
	v_add_f32_e32 v69, 1.0, v69
	v_pk_fma_f32 v[78:79], v[78:79], v[82:83], v[80:81]
	v_lshlrev_b32_e32 v80, 16, v142
	v_and_b32_e32 v81, 0xffff0000, v142
	v_lshlrev_b32_e32 v82, 16, v138
	v_and_b32_e32 v83, 0xffff0000, v138
	v_rcp_f32_e32 v68, v68
	v_rcp_f32_e32 v69, v69
	v_add_f32_e32 v70, 1.0, v70
	v_add_f32_e32 v71, 1.0, v71
	v_pk_fma_f32 v[72:73], v[72:73], v[82:83], v[80:81]
; __device__ __forceinline__ float bflo(unsigned u) { return __uint_as_float(u << 16); }
;     __device__ __forceinline__ void operator()(const Acc& acc, const Unit& u, int wr, int wc, int fr, int fq) const {
;     ...
;             for (int m = 0; m < 4; ++m) { const int row = u.pm * 256 + ai * 128 + wr * 64 + m * 16 + fr; const size_t off = (size_t)row * DM + colbase;
;                 rsv[m] = rowss[row];
; #pragma unroll
;                 for (int bj = 0; bj < 2; ++bj) { const u32x4 hw = __builtin_nontemporal_load((const u32x4*)(hin + off + 32 * bj));
;                     hv[m][bj][0] = (f32x4){bflo(hw.x), bfhi(hw.x), bflo(hw.y), bfhi(hw.y)}; hv[m][bj][1] = (f32x4){bflo(hw.z), bfhi(hw.z), bflo(hw.w), bfhi(hw.w)};
;                     pw[m][bj] = __builtin_nontemporal_load((const u32x4*)(PP + off + 32 * bj)); } }
; #pragma unroll
;             for (int m = 0; m < 4; ++m) {
;                 const int row = u.pm * 256 + ai * 128 + wr * 64 + m * 16 + fr;
;                 const float rs = rsqrtf(rsv[m] * (1.0f / DM) + EPS) * -1.4426950408889634f;
; #pragma unroll
;                 for (int bj = 0; bj < 2; ++bj) {
;                     const size_t off = (size_t)row * DM + colbase + 32 * bj;
;                     f32x4 h0 = hv[m][bj][0], h1 = hv[m][bj][1];
;                     const u32x4 p4 = pw[m][bj];
;                     const f32x4 a0 = acc[ai][bj][m][0], a1 = acc[ai][bj][m][1];
;                     h0.x += bflo(p4.x) * __builtin_amdgcn_rcpf(1.0f + __builtin_amdgcn_exp2f(a0.x * rs));
;                     h0.y += bfhi(p4.x) * __builtin_amdgcn_rcpf(1.0f + __builtin_amdgcn_exp2f(a0.y * rs));
;                     h0.z += bflo(p4.y) * __builtin_amdgcn_rcpf(1.0f + __builtin_amdgcn_exp2f(a0.z * rs));
;                     h0.w += bfhi(p4.y) * __builtin_amdgcn_rcpf(1.0f + __builtin_amdgcn_exp2f(a0.w * rs));
;                     h1.x += bflo(p4.z) * __builtin_amdgcn_rcpf(1.0f + __builtin_amdgcn_exp2f(a1.x * rs));
;                     h1.y += bfhi(p4.z) * __builtin_amdgcn_rcpf(1.0f + __builtin_amdgcn_exp2f(a1.y * rs));
;                     h1.z += bflo(p4.w) * __builtin_amdgcn_rcpf(1.0f + __builtin_amdgcn_exp2f(a1.z * rs));
;                     h1.w += bfhi(p4.w) * __builtin_amdgcn_rcpf(1.0f + __builtin_amdgcn_exp2f(a1.w * rs));
;                     *(f32x4*)(out + off) = h0; *(f32x4*)(out + off + 4) = h1;
	v_lshlrev_b32_e32 v80, 16, v143
	v_and_b32_e32 v81, 0xffff0000, v143
	v_lshlrev_b32_e32 v82, 16, v139
	v_and_b32_e32 v83, 0xffff0000, v139
	v_rcp_f32_e32 v70, v70
	v_rcp_f32_e32 v71, v71
	v_add_f32_e32 v64, 1.0, v64
	v_add_f32_e32 v65, 1.0, v65
	v_pk_fma_f32 v[74:75], v[74:75], v[82:83], v[80:81]
	v_lshl_add_u64 v[80:81], v[194:195], 2, s[2:3]
	v_rcp_f32_e32 v64, v64
	v_rcp_f32_e32 v65, v65
	v_add_f32_e32 v66, 1.0, v66
	v_add_f32_e32 v67, 1.0, v67
	flat_store_dwordx4 v[80:81], v[72:75] offset:16
	v_rcp_f32_e32 v66, v66
	v_rcp_f32_e32 v67, v67
	v_lshlrev_b32_e32 v72, 16, v132
	v_and_b32_e32 v73, 0xffff0000, v132
	v_lshlrev_b32_e32 v74, 16, v128
	v_and_b32_e32 v75, 0xffff0000, v128
	v_pk_fma_f32 v[68:69], v[68:69], v[74:75], v[72:73]
	v_lshlrev_b32_e32 v72, 16, v133
	v_and_b32_e32 v73, 0xffff0000, v133
	v_lshlrev_b32_e32 v74, 16, v129
	v_and_b32_e32 v75, 0xffff0000, v129
	v_pk_fma_f32 v[70:71], v[70:71], v[74:75], v[72:73]
	v_lshlrev_b32_e32 v72, 16, v134
	v_and_b32_e32 v73, 0xffff0000, v134
	v_lshlrev_b32_e32 v74, 16, v130
	v_and_b32_e32 v75, 0xffff0000, v130
	v_pk_fma_f32 v[64:65], v[64:65], v[74:75], v[72:73]
	v_lshlrev_b32_e32 v72, 16, v135
	v_and_b32_e32 v73, 0xffff0000, v135
	v_lshlrev_b32_e32 v74, 16, v131
	v_and_b32_e32 v75, 0xffff0000, v131
	flat_store_dwordx4 v[80:81], v[76:79]
	v_pk_fma_f32 v[66:67], v[66:67], v[74:75], v[72:73]
	flat_store_dwordx4 v[80:81], v[68:71] offset:128
	flat_store_dwordx4 v[80:81], v[64:67] offset:144
	flat_load_dword v68, v[192:193] offset:512
	s_nop 0
	v_add_u32_e32 v64, 0x80, v190
	v_ashrrev_i32_e32 v65, 31, v64
	v_lshlrev_b64 v[64:65], 11, v[64:65]
	v_lshl_add_u64 v[136:137], v[64:65], 0, v[188:189]
	v_lshlrev_b64 v[64:65], 1, v[136:137]
	v_lshl_add_u64 v[66:67], s[6:7], 0, v[64:65]
	v_lshl_add_u64 v[64:65], s[8:9], 0, v[64:65]
	v_mov_b64_e32 v[124:125], v[248:249]
	v_mov_b64_e32 v[126:127], v[252:253]
	flat_load_dwordx4 v[128:131], v[64:65] nt
	v_mov_b64_e32 v[132:133], v[236:237]
	v_mov_b64_e32 v[134:135], v[238:239]
	flat_load_dwordx4 v[112:115], v[64:65] offset:64 nt
	v_add_u32_e32 v64, 0x90, v190
	v_ashrrev_i32_e32 v65, 31, v64
	v_lshlrev_b64 v[64:65], 11, v[64:65]
	v_lshl_add_u64 v[120:121], v[64:65], 0, v[188:189]
	v_lshlrev_b64 v[64:65], 1, v[120:121]
	v_lshl_add_u64 v[66:67], s[6:7], 0, v[64:65]
	v_lshl_add_u64 v[64:65], s[8:9], 0, v[64:65]
	v_mov_b64_e32 v[108:109], v[240:241]
	v_mov_b64_e32 v[110:111], v[250:251]
	flat_load_dwordx4 v[100:103], v[66:67] offset:64 nt
	flat_load_dwordx4 v[104:107], v[64:65] nt
	flat_load_dwordx4 v[96:99], v[64:65] offset:64 nt
	v_add_u32_e32 v64, 0xa0, v190
	v_ashrrev_i32_e32 v65, 31, v64
	v_lshlrev_b64 v[64:65], 11, v[64:65]
	v_lshl_add_u64 v[118:119], v[64:65], 0, v[188:189]
	v_lshlrev_b64 v[64:65], 1, v[118:119]
	v_lshl_add_u64 v[66:67], s[6:7], 0, v[64:65]
	v_lshl_add_u64 v[64:65], s[8:9], 0, v[64:65]
	flat_load_dwordx4 v[92:95], v[66:67] nt
	flat_load_dwordx4 v[84:87], v[66:67] offset:64 nt
	flat_load_dwordx4 v[88:91], v[64:65] nt
	flat_load_dwordx4 v[80:83], v[64:65] offset:64 nt
	flat_load_dword v123, v[192:193] offset:576
	flat_load_dword v142, v[192:193] offset:640
	flat_load_dword v122, v[192:193] offset:704
	v_add_u32_e32 v64, 0xb0, v190
	v_ashrrev_i32_e32 v65, 31, v64
	v_lshlrev_b64 v[64:65], 11, v[64:65]
	v_lshl_add_u64 v[116:117], v[64:65], 0, v[188:189]
	v_lshlrev_b64 v[64:65], 1, v[116:117]
	v_lshl_add_u64 v[66:67], s[6:7], 0, v[64:65]
	s_waitcnt vmcnt(0) lgkmcnt(0)
	v_fmamk_f32 v68, v68, 0x3a000000, v205
	v_mul_f32_e32 v69, 0x4b800000, v68
	v_cmp_gt_f32_e32 vcc, s40, v68
	v_lshlrev_b32_e32 v140, 16, v128
	s_nop 0
	v_cndmask_b32_e32 v68, v68, v69, vcc
	v_rsq_f32_e32 v70, v68
	v_lshl_add_u64 v[68:69], s[8:9], 0, v[64:65]
	v_lshlrev_b32_e32 v138, 16, v124
	v_and_b32_e32 v139, 0xffff0000, v124
	v_mul_f32_e32 v71, 0x45800000, v70
	v_cndmask_b32_e32 v70, v70, v71, vcc
	v_mul_f32_e32 v143, 0xbfb8aa3b, v70
	v_mul_f32_e32 v62, v62, v143
	v_mul_f32_e32 v63, v63, v143
	v_exp_f32_e32 v62, v62
	v_exp_f32_e32 v63, v63
	v_mul_f32_e32 v56, v56, v143
	v_mul_f32_e32 v57, v57, v143
	v_exp_f32_e32 v56, v56
	v_exp_f32_e32 v57, v57
	v_mul_f32_e32 v58, v58, v143
	v_mul_f32_e32 v59, v59, v143
	v_exp_f32_e32 v58, v58
	v_exp_f32_e32 v59, v59
	v_mul_f32_e32 v52, v52, v143
	v_mul_f32_e32 v53, v53, v143
	v_add_f32_e32 v62, 1.0, v62
	v_add_f32_e32 v63, 1.0, v63
	v_exp_f32_e32 v52, v52
	v_exp_f32_e32 v53, v53
	v_mul_f32_e32 v54, v54, v143
	v_mul_f32_e32 v55, v55, v143
	v_mul_f32_e32 v60, v60, v143
	v_mul_f32_e32 v61, v61, v143
	v_rcp_f32_e32 v62, v62
	v_rcp_f32_e32 v63, v63
	v_add_f32_e32 v56, 1.0, v56
	v_add_f32_e32 v57, 1.0, v57
	v_exp_f32_e32 v54, v54
	v_exp_f32_e32 v55, v55
	v_mul_f32_e32 v48, v48, v143
	v_mul_f32_e32 v49, v49, v143
	v_exp_f32_e32 v60, v60
	v_exp_f32_e32 v61, v61
	v_rcp_f32_e32 v56, v56
	v_rcp_f32_e32 v57, v57
	v_add_f32_e32 v58, 1.0, v58
	v_add_f32_e32 v59, 1.0, v59
	v_exp_f32_e32 v48, v48
	v_exp_f32_e32 v49, v49
	v_rcp_f32_e32 v58, v58
	v_rcp_f32_e32 v59, v59
	v_and_b32_e32 v141, 0xffff0000, v128
	v_lshlrev_b32_e32 v124, 16, v125
	v_and_b32_e32 v125, 0xffff0000, v125
	v_lshlrev_b32_e32 v128, 16, v129
	v_and_b32_e32 v129, 0xffff0000, v129
	v_add_f32_e32 v52, 1.0, v52
	v_add_f32_e32 v53, 1.0, v53
	flat_load_dwordx4 v[72:75], v[66:67] nt
	s_nop 0
	flat_load_dwordx4 v[64:67], v[66:67] offset:64 nt
	s_nop 0
	flat_load_dwordx4 v[76:79], v[68:69] nt
	s_nop 0
	flat_load_dwordx4 v[68:71], v[68:69] offset:64 nt
	v_pk_fma_f32 v[62:63], v[62:63], v[128:129], v[124:125]
	v_lshlrev_b32_e32 v124, 16, v126
	v_and_b32_e32 v125, 0xffff0000, v126
	v_lshlrev_b32_e32 v128, 16, v130
	v_and_b32_e32 v129, 0xffff0000, v130
	v_rcp_f32_e32 v52, v52
	v_rcp_f32_e32 v53, v53
; __device__ __forceinline__ float bflo(unsigned u) { return __uint_as_float(u << 16); }
; __device__ __forceinline__ float bfhi(unsigned u) { return __uint_as_float(u & 0xffff0000u); }
;     __device__ __forceinline__ void operator()(const Acc& acc, const Unit& u, int wr, int wc, int fr, int fq) const {
;     ...
;             for (int m = 0; m < 4; ++m) {
;                 const int row = u.pm * 256 + ai * 128 + wr * 64 + m * 16 + fr;
;                 const float rs = rsqrtf(rsv[m] * (1.0f / DM) + EPS) * -1.4426950408889634f;
; #pragma unroll
;                 for (int bj = 0; bj < 2; ++bj) {
;                     const size_t off = (size_t)row * DM + colbase + 32 * bj;
;                     f32x4 h0 = hv[m][bj][0], h1 = hv[m][bj][1];
;                     const u32x4 p4 = pw[m][bj];
;                     const f32x4 a0 = acc[ai][bj][m][0], a1 = acc[ai][bj][m][1];
;                     h0.x += bflo(p4.x) * __builtin_amdgcn_rcpf(1.0f + __builtin_amdgcn_exp2f(a0.x * rs));
;                     h0.y += bfhi(p4.x) * __builtin_amdgcn_rcpf(1.0f + __builtin_amdgcn_exp2f(a0.y * rs));
;                     h0.z += bflo(p4.y) * __builtin_amdgcn_rcpf(1.0f + __builtin_amdgcn_exp2f(a0.z * rs));
;                     h0.w += bfhi(p4.y) * __builtin_amdgcn_rcpf(1.0f + __builtin_amdgcn_exp2f(a0.w * rs));
;                     h1.x += bflo(p4.z) * __builtin_amdgcn_rcpf(1.0f + __builtin_amdgcn_exp2f(a1.x * rs));
;                     h1.y += bfhi(p4.z) * __builtin_amdgcn_rcpf(1.0f + __builtin_amdgcn_exp2f(a1.y * rs));
;                     h1.z += bflo(p4.w) * __builtin_amdgcn_rcpf(1.0f + __builtin_amdgcn_exp2f(a1.z * rs));
;                     h1.w += bfhi(p4.w) * __builtin_amdgcn_rcpf(1.0f + __builtin_amdgcn_exp2f(a1.w * rs));
;                     *(f32x4*)(out + off) = h0; *(f32x4*)(out + off + 4) = h1;
	v_add_f32_e32 v54, 1.0, v54
	v_add_f32_e32 v55, 1.0, v55
	v_add_f32_e32 v60, 1.0, v60
	v_add_f32_e32 v61, 1.0, v61
	v_pk_fma_f32 v[56:57], v[56:57], v[128:129], v[124:125]
	v_lshlrev_b32_e32 v124, 16, v127
	v_and_b32_e32 v125, 0xffff0000, v127
	v_lshlrev_b32_e32 v126, 16, v131
	v_and_b32_e32 v127, 0xffff0000, v131
	v_rcp_f32_e32 v54, v54
	v_rcp_f32_e32 v55, v55
	v_add_f32_e32 v48, 1.0, v48
	v_add_f32_e32 v49, 1.0, v49
	v_rcp_f32_e32 v60, v60
	v_rcp_f32_e32 v61, v61
	v_pk_fma_f32 v[58:59], v[58:59], v[126:127], v[124:125]
	v_lshl_add_u64 v[124:125], v[136:137], 2, s[2:3]
	v_rcp_f32_e32 v48, v48
	v_rcp_f32_e32 v49, v49
	flat_store_dwordx4 v[124:125], v[56:59] offset:16
	v_pk_fma_f32 v[60:61], v[60:61], v[140:141], v[138:139]
	flat_store_dwordx4 v[124:125], v[60:63]
	v_lshlrev_b32_e32 v56, 16, v132
	v_and_b32_e32 v57, 0xffff0000, v132
	v_lshlrev_b32_e32 v58, 16, v112
	v_and_b32_e32 v59, 0xffff0000, v112
	v_pk_fma_f32 v[52:53], v[52:53], v[58:59], v[56:57]
	v_lshlrev_b32_e32 v56, 16, v133
	v_and_b32_e32 v57, 0xffff0000, v133
	v_lshlrev_b32_e32 v58, 16, v113
	v_and_b32_e32 v59, 0xffff0000, v113
	v_pk_fma_f32 v[54:55], v[54:55], v[58:59], v[56:57]
	v_lshlrev_b32_e32 v56, 16, v134
	v_and_b32_e32 v57, 0xffff0000, v134
	v_lshlrev_b32_e32 v58, 16, v114
	v_and_b32_e32 v59, 0xffff0000, v114
	v_pk_fma_f32 v[48:49], v[48:49], v[58:59], v[56:57]
	v_fmamk_f32 v59, v123, 0x3a000000, v205
	v_mul_f32_e32 v60, 0x4b800000, v59
	v_cmp_gt_f32_e32 vcc, s40, v59
	flat_store_dwordx4 v[124:125], v[52:55] offset:128
	v_mul_f32_e32 v50, v50, v143
	v_cndmask_b32_e32 v59, v59, v60, vcc
	v_rsq_f32_e32 v60, v59
	v_mul_f32_e32 v51, v51, v143
	v_exp_f32_e32 v50, v50
	v_exp_f32_e32 v51, v51
	v_mul_f32_e32 v52, 0x45800000, v60
	v_cndmask_b32_e32 v52, v60, v52, vcc
	v_mul_f32_e32 v52, 0xbfb8aa3b, v52
	v_mul_f32_e32 v44, v44, v52
	v_mul_f32_e32 v45, v45, v52
	v_exp_f32_e32 v44, v44
	v_exp_f32_e32 v45, v45
	v_mul_f32_e32 v46, v46, v52
	v_mul_f32_e32 v47, v47, v52
	v_exp_f32_e32 v46, v46
	v_exp_f32_e32 v47, v47
	v_mul_f32_e32 v40, v40, v52
	v_mul_f32_e32 v41, v41, v52
	v_add_f32_e32 v50, 1.0, v50
	v_add_f32_e32 v51, 1.0, v51
	v_exp_f32_e32 v40, v40
	v_exp_f32_e32 v41, v41
	v_mul_f32_e32 v42, v42, v52
	v_mul_f32_e32 v43, v43, v52
	v_rcp_f32_e32 v50, v50
	v_rcp_f32_e32 v51, v51
	v_exp_f32_e32 v42, v42
	v_exp_f32_e32 v43, v43
	v_add_f32_e32 v44, 1.0, v44
	v_add_f32_e32 v45, 1.0, v45
	v_mul_f32_e32 v36, v36, v52
	v_mul_f32_e32 v37, v37, v52
	v_rcp_f32_e32 v44, v44
	v_rcp_f32_e32 v45, v45
	v_add_f32_e32 v46, 1.0, v46
	v_add_f32_e32 v47, 1.0, v47
	v_exp_f32_e32 v36, v36
	v_exp_f32_e32 v37, v37
	v_mul_f32_e32 v38, v38, v52
	v_mul_f32_e32 v39, v39, v52
	v_lshlrev_b32_e32 v56, 16, v135
	v_and_b32_e32 v57, 0xffff0000, v135
	v_lshlrev_b32_e32 v58, 16, v115
	v_and_b32_e32 v59, 0xffff0000, v115
	v_rcp_f32_e32 v46, v46
	v_rcp_f32_e32 v47, v47
	v_add_f32_e32 v40, 1.0, v40
	v_add_f32_e32 v41, 1.0, v41
	v_exp_f32_e32 v38, v38
	v_exp_f32_e32 v39, v39
	v_mul_f32_e32 v32, v32, v52
	v_mul_f32_e32 v33, v33, v52
	v_pk_fma_f32 v[50:51], v[50:51], v[58:59], v[56:57]
	v_rcp_f32_e32 v40, v40
	v_rcp_f32_e32 v41, v41
	v_add_f32_e32 v42, 1.0, v42
	v_add_f32_e32 v43, 1.0, v43
	v_exp_f32_e32 v32, v32
	v_exp_f32_e32 v33, v33
	flat_store_dwordx4 v[124:125], v[48:51] offset:144
	v_rcp_f32_e32 v42, v42
	v_rcp_f32_e32 v43, v43
	v_lshlrev_b32_e32 v48, 16, v108
	v_and_b32_e32 v49, 0xffff0000, v108
	v_lshlrev_b32_e32 v50, 16, v104
	v_and_b32_e32 v51, 0xffff0000, v104
	v_pk_fma_f32 v[44:45], v[44:45], v[50:51], v[48:49]
	v_lshlrev_b32_e32 v48, 16, v109
	v_and_b32_e32 v49, 0xffff0000, v109
	v_lshlrev_b32_e32 v50, 16, v105
	v_and_b32_e32 v51, 0xffff0000, v105
	v_add_f32_e32 v36, 1.0, v36
	v_add_f32_e32 v37, 1.0, v37
	v_pk_fma_f32 v[46:47], v[46:47], v[50:51], v[48:49]
	v_lshlrev_b32_e32 v48, 16, v110
	v_and_b32_e32 v49, 0xffff0000, v110
	v_lshlrev_b32_e32 v50, 16, v106
	v_and_b32_e32 v51, 0xffff0000, v106
	v_rcp_f32_e32 v36, v36
	v_rcp_f32_e32 v37, v37
	v_add_f32_e32 v38, 1.0, v38
	v_add_f32_e32 v39, 1.0, v39
	v_pk_fma_f32 v[40:41], v[40:41], v[50:51], v[48:49]
	v_lshlrev_b32_e32 v48, 16, v111
	v_and_b32_e32 v49, 0xffff0000, v111
	v_lshlrev_b32_e32 v50, 16, v107
	v_and_b32_e32 v51, 0xffff0000, v107
	v_rcp_f32_e32 v38, v38
	v_rcp_f32_e32 v39, v39
	v_add_f32_e32 v32, 1.0, v32
	v_add_f32_e32 v33, 1.0, v33
	v_pk_fma_f32 v[42:43], v[42:43], v[50:51], v[48:49]
	v_lshl_add_u64 v[48:49], v[120:121], 2, s[2:3]
	v_rcp_f32_e32 v32, v32
	v_rcp_f32_e32 v33, v33
	flat_store_dwordx4 v[48:49], v[40:43] offset:16
	flat_store_dwordx4 v[48:49], v[44:47]
	v_mul_f32_e32 v34, v34, v52
	v_lshlrev_b32_e32 v40, 16, v100
	v_and_b32_e32 v41, 0xffff0000, v100
	v_lshlrev_b32_e32 v42, 16, v96
	v_and_b32_e32 v43, 0xffff0000, v96
	v_pk_fma_f32 v[36:37], v[36:37], v[42:43], v[40:41]
	v_lshlrev_b32_e32 v40, 16, v101
	v_and_b32_e32 v41, 0xffff0000, v101
	v_lshlrev_b32_e32 v42, 16, v97
	v_and_b32_e32 v43, 0xffff0000, v97
	v_pk_fma_f32 v[38:39], v[38:39], v[42:43], v[40:41]
	v_lshlrev_b32_e32 v40, 16, v102
	v_and_b32_e32 v41, 0xffff0000, v102
	v_lshlrev_b32_e32 v42, 16, v98
	v_and_b32_e32 v43, 0xffff0000, v98
	v_pk_fma_f32 v[32:33], v[32:33], v[42:43], v[40:41]
	v_fmamk_f32 v43, v142, 0x3a000000, v205
	v_mul_f32_e32 v44, 0x4b800000, v43
	v_cmp_gt_f32_e32 vcc, s40, v43
	flat_store_dwordx4 v[48:49], v[36:39] offset:128
	v_mul_f32_e32 v35, v35, v52
	v_cndmask_b32_e32 v43, v43, v44, vcc
	v_rsq_f32_e32 v44, v43
	v_exp_f32_e32 v34, v34
	v_exp_f32_e32 v35, v35
	v_lshlrev_b32_e32 v40, 16, v103
	v_mul_f32_e32 v36, 0x45800000, v44
	v_cndmask_b32_e32 v36, v44, v36, vcc
	v_mul_f32_e32 v36, 0xbfb8aa3b, v36
	v_mul_f32_e32 v28, v28, v36
	v_mul_f32_e32 v29, v29, v36
; __device__ __forceinline__ float bflo(unsigned u) { return __uint_as_float(u << 16); }
; __device__ __forceinline__ float bfhi(unsigned u) { return __uint_as_float(u & 0xffff0000u); }
;     __device__ __forceinline__ void operator()(const Acc& acc, const Unit& u, int wr, int wc, int fr, int fq) const {
;     ...
;             for (int m = 0; m < 4; ++m) {
;                 const int row = u.pm * 256 + ai * 128 + wr * 64 + m * 16 + fr;
;                 const float rs = rsqrtf(rsv[m] * (1.0f / DM) + EPS) * -1.4426950408889634f;
; #pragma unroll
;                 for (int bj = 0; bj < 2; ++bj) {
;                     const size_t off = (size_t)row * DM + colbase + 32 * bj;
;                     f32x4 h0 = hv[m][bj][0], h1 = hv[m][bj][1];
;                     const u32x4 p4 = pw[m][bj];
;                     const f32x4 a0 = acc[ai][bj][m][0], a1 = acc[ai][bj][m][1];
;                     h0.x += bflo(p4.x) * __builtin_amdgcn_rcpf(1.0f + __builtin_amdgcn_exp2f(a0.x * rs));
;                     h0.y += bfhi(p4.x) * __builtin_amdgcn_rcpf(1.0f + __builtin_amdgcn_exp2f(a0.y * rs));
;                     h0.z += bflo(p4.y) * __builtin_amdgcn_rcpf(1.0f + __builtin_amdgcn_exp2f(a0.z * rs));
;                     h0.w += bfhi(p4.y) * __builtin_amdgcn_rcpf(1.0f + __builtin_amdgcn_exp2f(a0.w * rs));
;                     h1.x += bflo(p4.z) * __builtin_amdgcn_rcpf(1.0f + __builtin_amdgcn_exp2f(a1.x * rs));
;                     h1.y += bfhi(p4.z) * __builtin_amdgcn_rcpf(1.0f + __builtin_amdgcn_exp2f(a1.y * rs));
;                     h1.z += bflo(p4.w) * __builtin_amdgcn_rcpf(1.0f + __builtin_amdgcn_exp2f(a1.z * rs));
;                     h1.w += bfhi(p4.w) * __builtin_amdgcn_rcpf(1.0f + __builtin_amdgcn_exp2f(a1.w * rs));
;                     *(f32x4*)(out + off) = h0; *(f32x4*)(out + off + 4) = h1;
	v_exp_f32_e32 v28, v28
	v_exp_f32_e32 v29, v29
	v_mul_f32_e32 v30, v30, v36
	v_mul_f32_e32 v31, v31, v36
	v_exp_f32_e32 v30, v30
	v_exp_f32_e32 v31, v31
	v_mul_f32_e32 v24, v24, v36
	v_mul_f32_e32 v25, v25, v36
	v_add_f32_e32 v34, 1.0, v34
	v_add_f32_e32 v35, 1.0, v35
	v_exp_f32_e32 v24, v24
	v_exp_f32_e32 v25, v25
	v_mul_f32_e32 v26, v26, v36
	v_mul_f32_e32 v27, v27, v36
	v_rcp_f32_e32 v34, v34
	v_rcp_f32_e32 v35, v35
	v_exp_f32_e32 v26, v26
	v_exp_f32_e32 v27, v27
	v_add_f32_e32 v28, 1.0, v28
	v_add_f32_e32 v29, 1.0, v29
	v_mul_f32_e32 v20, v20, v36
	v_mul_f32_e32 v21, v21, v36
	v_rcp_f32_e32 v28, v28
	v_rcp_f32_e32 v29, v29
	v_add_f32_e32 v30, 1.0, v30
	v_add_f32_e32 v31, 1.0, v31
	v_exp_f32_e32 v20, v20
	v_exp_f32_e32 v21, v21
	v_mul_f32_e32 v22, v22, v36
	v_mul_f32_e32 v23, v23, v36
	v_and_b32_e32 v41, 0xffff0000, v103
	v_lshlrev_b32_e32 v42, 16, v99
	v_and_b32_e32 v43, 0xffff0000, v99
	v_rcp_f32_e32 v30, v30
	v_rcp_f32_e32 v31, v31
	v_add_f32_e32 v24, 1.0, v24
	v_add_f32_e32 v25, 1.0, v25
	v_exp_f32_e32 v22, v22
	v_exp_f32_e32 v23, v23
	v_mul_f32_e32 v16, v16, v36
	v_mul_f32_e32 v17, v17, v36
	v_pk_fma_f32 v[34:35], v[34:35], v[42:43], v[40:41]
	v_rcp_f32_e32 v24, v24
	v_rcp_f32_e32 v25, v25
	v_add_f32_e32 v26, 1.0, v26
	v_add_f32_e32 v27, 1.0, v27
	v_exp_f32_e32 v16, v16
	v_exp_f32_e32 v17, v17
	flat_store_dwordx4 v[48:49], v[32:35] offset:144
	v_rcp_f32_e32 v26, v26
	v_rcp_f32_e32 v27, v27
	v_lshlrev_b32_e32 v32, 16, v92
	v_and_b32_e32 v33, 0xffff0000, v92
	v_lshlrev_b32_e32 v34, 16, v88
	v_and_b32_e32 v35, 0xffff0000, v88
	v_pk_fma_f32 v[28:29], v[28:29], v[34:35], v[32:33]
	v_lshlrev_b32_e32 v32, 16, v93
	v_and_b32_e32 v33, 0xffff0000, v93
	v_lshlrev_b32_e32 v34, 16, v89
	v_and_b32_e32 v35, 0xffff0000, v89
	v_add_f32_e32 v20, 1.0, v20
	v_add_f32_e32 v21, 1.0, v21
	v_pk_fma_f32 v[30:31], v[30:31], v[34:35], v[32:33]
	v_lshlrev_b32_e32 v32, 16, v94
	v_and_b32_e32 v33, 0xffff0000, v94
	v_lshlrev_b32_e32 v34, 16, v90
	v_and_b32_e32 v35, 0xffff0000, v90
	v_rcp_f32_e32 v20, v20
	v_rcp_f32_e32 v21, v21
	v_add_f32_e32 v22, 1.0, v22
	v_add_f32_e32 v23, 1.0, v23
	v_pk_fma_f32 v[24:25], v[24:25], v[34:35], v[32:33]
	v_lshlrev_b32_e32 v32, 16, v95
	v_and_b32_e32 v33, 0xffff0000, v95
	v_lshlrev_b32_e32 v34, 16, v91
	v_and_b32_e32 v35, 0xffff0000, v91
	v_rcp_f32_e32 v22, v22
	v_rcp_f32_e32 v23, v23
	v_add_f32_e32 v16, 1.0, v16
	v_add_f32_e32 v17, 1.0, v17
	v_pk_fma_f32 v[26:27], v[26:27], v[34:35], v[32:33]
	v_lshl_add_u64 v[32:33], v[118:119], 2, s[2:3]
	v_rcp_f32_e32 v16, v16
	v_rcp_f32_e32 v17, v17
	flat_store_dwordx4 v[32:33], v[24:27] offset:16
	flat_store_dwordx4 v[32:33], v[28:31]
	v_mul_f32_e32 v18, v18, v36
	v_lshlrev_b32_e32 v24, 16, v84
	v_and_b32_e32 v25, 0xffff0000, v84
	v_lshlrev_b32_e32 v26, 16, v80
	v_and_b32_e32 v27, 0xffff0000, v80
	v_pk_fma_f32 v[20:21], v[20:21], v[26:27], v[24:25]
	v_lshlrev_b32_e32 v24, 16, v85
	v_and_b32_e32 v25, 0xffff0000, v85
	v_lshlrev_b32_e32 v26, 16, v81
	v_and_b32_e32 v27, 0xffff0000, v81
	v_pk_fma_f32 v[22:23], v[22:23], v[26:27], v[24:25]
	v_lshlrev_b32_e32 v24, 16, v86
	v_and_b32_e32 v25, 0xffff0000, v86
	v_lshlrev_b32_e32 v26, 16, v82
	v_and_b32_e32 v27, 0xffff0000, v82
	v_pk_fma_f32 v[16:17], v[16:17], v[26:27], v[24:25]
	v_fmamk_f32 v27, v122, 0x3a000000, v205
	v_mul_f32_e32 v28, 0x4b800000, v27
	v_cmp_gt_f32_e32 vcc, s40, v27
	flat_store_dwordx4 v[32:33], v[20:23] offset:128
	v_mul_f32_e32 v19, v19, v36
	v_cndmask_b32_e32 v27, v27, v28, vcc
	v_rsq_f32_e32 v28, v27
	v_exp_f32_e32 v18, v18
	v_exp_f32_e32 v19, v19
	v_lshlrev_b32_e32 v24, 16, v87
	v_mul_f32_e32 v20, 0x45800000, v28
	v_cndmask_b32_e32 v20, v28, v20, vcc
	v_mul_f32_e32 v20, 0xbfb8aa3b, v20
	v_mul_f32_e32 v12, v12, v20
	v_mul_f32_e32 v13, v13, v20
	v_exp_f32_e32 v12, v12
	v_exp_f32_e32 v13, v13
	v_mul_f32_e32 v14, v14, v20
	v_mul_f32_e32 v15, v15, v20
	v_exp_f32_e32 v14, v14
	v_exp_f32_e32 v15, v15
	v_mul_f32_e32 v8, v8, v20
	v_mul_f32_e32 v9, v9, v20
	v_add_f32_e32 v18, 1.0, v18
	v_add_f32_e32 v19, 1.0, v19
	v_exp_f32_e32 v8, v8
	v_exp_f32_e32 v9, v9
	v_mul_f32_e32 v10, v10, v20
	v_mul_f32_e32 v11, v11, v20
	v_rcp_f32_e32 v18, v18
	v_rcp_f32_e32 v19, v19
	v_exp_f32_e32 v10, v10
	v_exp_f32_e32 v11, v11
	v_add_f32_e32 v12, 1.0, v12
	v_add_f32_e32 v13, 1.0, v13
	v_mul_f32_e32 v4, v4, v20
	v_mul_f32_e32 v5, v5, v20
	v_rcp_f32_e32 v12, v12
	v_rcp_f32_e32 v13, v13
	v_add_f32_e32 v14, 1.0, v14
	v_add_f32_e32 v15, 1.0, v15
	v_exp_f32_e32 v4, v4
	v_exp_f32_e32 v5, v5
	v_mul_f32_e32 v6, v6, v20
	v_mul_f32_e32 v7, v7, v20
	v_and_b32_e32 v25, 0xffff0000, v87
	v_lshlrev_b32_e32 v26, 16, v83
	v_and_b32_e32 v27, 0xffff0000, v83
	v_rcp_f32_e32 v14, v14
	v_rcp_f32_e32 v15, v15
	v_add_f32_e32 v8, 1.0, v8
	v_add_f32_e32 v9, 1.0, v9
	v_exp_f32_e32 v6, v6
	v_exp_f32_e32 v7, v7
	v_mul_f32_e32 v0, v0, v20
	v_mul_f32_e32 v1, v1, v20
	v_pk_fma_f32 v[18:19], v[18:19], v[26:27], v[24:25]
	v_rcp_f32_e32 v8, v8
	v_rcp_f32_e32 v9, v9
	v_add_f32_e32 v10, 1.0, v10
	v_add_f32_e32 v11, 1.0, v11
	v_exp_f32_e32 v0, v0
	v_exp_f32_e32 v1, v1
	v_mul_f32_e32 v2, v2, v20
	v_mul_f32_e32 v3, v3, v20
	flat_store_dwordx4 v[32:33], v[16:19] offset:144
	v_rcp_f32_e32 v10, v10
	v_rcp_f32_e32 v11, v11
	s_waitcnt vmcnt(0) lgkmcnt(0)
; __device__ __forceinline__ float bflo(unsigned u) { return __uint_as_float(u << 16); }
; __device__ __forceinline__ float bfhi(unsigned u) { return __uint_as_float(u & 0xffff0000u); }
; #define PG8_BAR __builtin_amdgcn_s_barrier()
; template <class Epi, bool ALIGN_EPI>
; __device__ __forceinline__ void gemm_phase(LAS unsigned char* lds, const Gemm g, const StaticOrder& S, const Epi& E, const int wid) {
;     ...
;         if (!has_next) break;
; #pragma unroll
;         for (int a = 0; a < 2; ++a)
; #pragma unroll
;             for (int b = 0; b < 2; ++b)
; #pragma unroll
;                 for (int m = 0; m < 4; ++m)
; #pragma unroll
;                     for (int n = 0; n < 2; ++n) acc[a][b][m][n] = (f32x4){0.f, 0.f, 0.f, 0.f};
;         cur = nxt; cA = nA; cB = nB; ++ui;
;         if constexpr (ALIGN_EPI) { if (wr == 1) PG8_BAR; }
;     __device__ __forceinline__ void operator()(const Acc& acc, const Unit& u, int wr, int wc, int fr, int fq) const {
;     ...
;                     h0.x += bflo(p4.x) * __builtin_amdgcn_rcpf(1.0f + __builtin_amdgcn_exp2f(a0.x * rs));
;                     h0.y += bfhi(p4.x) * __builtin_amdgcn_rcpf(1.0f + __builtin_amdgcn_exp2f(a0.y * rs));
;                     h0.z += bflo(p4.y) * __builtin_amdgcn_rcpf(1.0f + __builtin_amdgcn_exp2f(a0.z * rs));
;                     h0.w += bfhi(p4.y) * __builtin_amdgcn_rcpf(1.0f + __builtin_amdgcn_exp2f(a0.w * rs));
;                     h1.x += bflo(p4.z) * __builtin_amdgcn_rcpf(1.0f + __builtin_amdgcn_exp2f(a1.x * rs));
;                     h1.y += bfhi(p4.z) * __builtin_amdgcn_rcpf(1.0f + __builtin_amdgcn_exp2f(a1.y * rs));
;                     h1.z += bflo(p4.w) * __builtin_amdgcn_rcpf(1.0f + __builtin_amdgcn_exp2f(a1.z * rs));
;                     h1.w += bfhi(p4.w) * __builtin_amdgcn_rcpf(1.0f + __builtin_amdgcn_exp2f(a1.w * rs));
;                     *(f32x4*)(out + off) = h0; *(f32x4*)(out + off + 4) = h1;
	v_lshlrev_b32_e32 v16, 16, v72
	v_and_b32_e32 v17, 0xffff0000, v72
	v_lshlrev_b32_e32 v18, 16, v76
	v_and_b32_e32 v19, 0xffff0000, v76
	v_exp_f32_e32 v2, v2
	v_exp_f32_e32 v3, v3
	v_pk_fma_f32 v[12:13], v[12:13], v[18:19], v[16:17]
	v_lshlrev_b32_e32 v16, 16, v73
	v_and_b32_e32 v17, 0xffff0000, v73
	v_lshlrev_b32_e32 v18, 16, v77
	v_and_b32_e32 v19, 0xffff0000, v77
	v_add_f32_e32 v4, 1.0, v4
	v_add_f32_e32 v5, 1.0, v5
	v_pk_fma_f32 v[14:15], v[14:15], v[18:19], v[16:17]
	v_lshlrev_b32_e32 v16, 16, v74
	v_and_b32_e32 v17, 0xffff0000, v74
	v_lshlrev_b32_e32 v18, 16, v78
	v_and_b32_e32 v19, 0xffff0000, v78
	v_rcp_f32_e32 v4, v4
	v_rcp_f32_e32 v5, v5
	v_add_f32_e32 v6, 1.0, v6
	v_add_f32_e32 v7, 1.0, v7
	v_pk_fma_f32 v[8:9], v[8:9], v[18:19], v[16:17]
	v_lshlrev_b32_e32 v16, 16, v75
	v_and_b32_e32 v17, 0xffff0000, v75
	v_lshlrev_b32_e32 v18, 16, v79
	v_and_b32_e32 v19, 0xffff0000, v79
	v_rcp_f32_e32 v6, v6
	v_rcp_f32_e32 v7, v7
	v_add_f32_e32 v0, 1.0, v0
	v_add_f32_e32 v1, 1.0, v1
	v_pk_fma_f32 v[10:11], v[10:11], v[18:19], v[16:17]
	v_lshl_add_u64 v[16:17], v[116:117], 2, s[2:3]
	v_rcp_f32_e32 v0, v0
	v_rcp_f32_e32 v1, v1
	v_add_f32_e32 v2, 1.0, v2
	v_add_f32_e32 v3, 1.0, v3
	flat_store_dwordx4 v[16:17], v[8:11] offset:16
	v_rcp_f32_e32 v2, v2
	v_rcp_f32_e32 v3, v3
	v_lshlrev_b32_e32 v8, 16, v64
	v_and_b32_e32 v9, 0xffff0000, v64
	v_lshlrev_b32_e32 v10, 16, v68
	v_and_b32_e32 v11, 0xffff0000, v68
	v_pk_fma_f32 v[4:5], v[4:5], v[10:11], v[8:9]
	v_lshlrev_b32_e32 v8, 16, v65
	v_and_b32_e32 v9, 0xffff0000, v65
	v_lshlrev_b32_e32 v10, 16, v69
	v_and_b32_e32 v11, 0xffff0000, v69
	v_pk_fma_f32 v[6:7], v[6:7], v[10:11], v[8:9]
	v_lshlrev_b32_e32 v8, 16, v66
	v_and_b32_e32 v9, 0xffff0000, v66
	v_lshlrev_b32_e32 v10, 16, v70
	v_and_b32_e32 v11, 0xffff0000, v70
	v_pk_fma_f32 v[0:1], v[0:1], v[10:11], v[8:9]
	v_lshlrev_b32_e32 v8, 16, v67
	v_and_b32_e32 v9, 0xffff0000, v67
	v_lshlrev_b32_e32 v10, 16, v71
	v_and_b32_e32 v11, 0xffff0000, v71
	s_andn2_b64 vcc, exec, s[4:5]
	s_mov_b64 s[4:5], -1
	flat_store_dwordx4 v[16:17], v[12:15]
	v_pk_fma_f32 v[2:3], v[2:3], v[10:11], v[8:9]
	flat_store_dwordx4 v[16:17], v[4:7] offset:128
	flat_store_dwordx4 v[16:17], v[0:3] offset:144
	s_cbranch_vccnz .LBB0_803
	s_and_b64 vcc, exec, s[0:1]
	s_cbranch_vccnz .LBB0_802
	s_barrier
	s_branch .LBB0_802
